# max-subtraction fold extended to the NSA selection-branch loop (per-tile -m / -inf accumulator init from the selection bit)
# baseline (speedup 1.0000x reference)
.LBB0_4380:
	s_or_b64 exec, exec, s[2:3]
	s_load_dwordx4 s[4:7], s[0:1], 0x1b8
	v_mov_b32_e32 v0, v169
	s_lshl_b64 s[10:11], s[50:51], 21
	s_waitcnt lgkmcnt(0)
	s_add_u32 s2, s4, s10
	v_add_u32_e32 v3, s70, v0
	v_ashrrev_i32_e32 v2, 31, v3
	s_addc_u32 s3, s5, s11
	s_lshl_b32 s8, s74, 7
	v_lshrrev_b32_e32 v2, 29, v2
	s_add_u32 s2, s2, s8
	v_add_u32_e32 v4, v3, v2
	s_addc_u32 s3, s3, 0
	v_ashrrev_i32_e32 v2, 3, v4
	v_and_b32_e32 v4, 0x1ffffff8, v4
	s_add_u32 s9, s6, s10
	v_sub_u32_e32 v3, v3, v4
	s_addc_u32 s12, s7, s11
	s_waitcnt vmcnt(10)
	v_lshlrev_b32_e32 v122, 3, v3
	v_ashrrev_i32_e32 v3, 31, v2
	s_add_u32 s8, s9, s8
	s_waitcnt vmcnt(9)
	v_lshlrev_b64 v[124:125], 9, v[2:3]
	v_ashrrev_i32_e32 v123, 31, v122
	s_addc_u32 s9, s12, 0
	v_lshl_add_u64 v[4:5], s[2:3], 0, v[124:125]
	v_lshlrev_b64 v[6:7], 1, v[122:123]
	v_lshl_add_u64 v[4:5], v[4:5], 0, v[6:7]
	v_lshl_add_u64 v[8:9], s[8:9], 0, v[124:125]
	v_lshl_add_u64 v[6:7], v[8:9], 0, v[6:7]
	global_load_dwordx4 v[112:115], v[4:5], off
	global_load_dwordx4 v[116:119], v[6:7], off
	s_sub_i32 s2, 0x103f, s72
	s_ashr_i32 s3, s2, 31
	s_lshr_b32 s3, s3, 26
	s_add_i32 s2, s2, s3
	s_ashr_i32 s8, s2, 6
	s_ashr_i32 s2, s75, 6
	s_add_i32 s3, s2, 1
	s_min_i32 s14, s3, s8
	s_cmp_lt_i32 s14, 1
	v_mul_lo_u32 v130, v2, s63
	v_mul_lo_u32 v131, v2, s64
	s_barrier
	s_cbranch_scc1 .LBB0_4390
	v_bfe_u32 v2, v0, 5, 1
	v_and_b32_e32 v3, 31, v0
	s_sub_i32 s3, s67, s73
	v_or_b32_e32 v132, s48, v3
	v_lshlrev_b32_e32 v133, 2, v2
	v_mul_u32_u24_e32 v66, 0x48, v3
	v_lshlrev_b32_e32 v135, 4, v2
	v_lshl_add_u64 v[2:3], s[10:11], 0, v[124:125]
	s_and_b32 s3, s3, 3
	v_lshrrev_b32_e32 v4, 2, v0
	v_lshl_or_b32 v2, s3, 7, v2
	s_ashr_i32 s3, s2, 31
	v_and_or_b32 v4, v4, 3, v133
	v_lshl_add_u64 v[2:3], v[122:123], 1, v[2:3]
	s_add_u32 s2, s2, 1
	v_mul_u32_u24_e32 v134, 0xc0, v4
	v_lshl_add_u64 v[4:5], s[4:5], 0, v[2:3]
	v_lshl_add_u64 v[2:3], s[6:7], 0, v[2:3]
	s_addc_u32 s3, s3, 0
	s_ashr_i32 s9, s8, 31
	v_and_b32_e32 v64, 16, v0
	v_lshlrev_b32_e32 v0, 2, v0
	v_lshl_add_u64 v[128:129], v[2:3], 0, s[36:37]
	v_mov_b64_e32 v[2:3], s[8:9]
	v_and_b32_e32 v65, 12, v0
	v_cmp_lt_i64_e32 vcc, s[2:3], v[2:3]
	v_mov_b32_e32 v30, v1
	v_mov_b32_e32 v31, v1
	v_lshl_add_u64 v[126:127], v[4:5], 0, s[36:37]
	s_and_b64 s[12:13], vcc, exec
	v_mov_b32_e32 v0, v1
	v_mov_b32_e32 v2, v1
	v_mov_b32_e32 v3, v1
	v_mov_b32_e32 v4, v1
	v_mov_b32_e32 v5, v1
	v_mov_b32_e32 v6, v1
	v_mov_b32_e32 v7, v1
	v_mov_b32_e32 v8, v1
	v_mov_b32_e32 v9, v1
	v_mov_b32_e32 v10, v1
	v_mov_b32_e32 v11, v1
	v_mov_b32_e32 v12, v1
	v_mov_b32_e32 v13, v1
	v_mov_b32_e32 v14, v1
	v_mov_b32_e32 v15, v1
	v_mov_b32_e32 v16, v1
	v_mov_b32_e32 v17, v1
	v_mov_b32_e32 v18, v1
	v_mov_b32_e32 v19, v1
	v_mov_b32_e32 v20, v1
	v_mov_b32_e32 v21, v1
	v_mov_b32_e32 v22, v1
	v_mov_b32_e32 v23, v1
	v_mov_b32_e32 v24, v1
	v_mov_b32_e32 v25, v1
	v_mov_b32_e32 v26, v1
	v_mov_b32_e32 v27, v1
	v_mov_b32_e32 v28, v1
	v_mov_b32_e32 v29, v1
	v_lshlrev_b32_e32 v136, 1, v66
	v_lshlrev_b32_e32 v137, 1, v64
	v_lshlrev_b32_e32 v138, 1, v65
	s_waitcnt vmcnt(2)
	v_mov_b64_e32 v[94:95], v[30:31]
	s_cselect_b32 s9, s2, s8
	v_mov_b32_e32 v189, 0
	v_mov_b32_e32 v139, 0xf149f2ca
	v_mov_b32_e32 v212, 0
	v_mov_b32_e32 v213, 0
	v_mov_b32_e32 v214, 0
	v_mov_b32_e32 v215, 0
	v_mov_b32_e32 v216, 0
	v_mov_b32_e32 v217, 0
	v_mov_b32_e32 v218, 0
	v_mov_b32_e32 v219, 0
	v_mov_b32_e32 v220, 0
	v_mov_b32_e32 v221, 0
	v_mov_b32_e32 v222, 0
	v_mov_b32_e32 v223, 0
	v_mov_b32_e32 v224, 0
	v_mov_b32_e32 v225, 0
	v_mov_b32_e32 v226, 0
	v_mov_b32_e32 v227, 0
	v_mov_b32_e32 v228, 0
	v_mov_b32_e32 v229, v139
	s_mov_b64 s[2:3], 0
	s_mov_b32 s15, 63
	v_mov_b64_e32 v[92:93], v[28:29]
	v_mov_b64_e32 v[90:91], v[26:27]
	v_mov_b64_e32 v[88:89], v[24:25]
	v_mov_b64_e32 v[86:87], v[22:23]
	v_mov_b64_e32 v[84:85], v[20:21]
	v_mov_b64_e32 v[82:83], v[18:19]
	v_mov_b64_e32 v[80:81], v[16:17]
	v_mov_b64_e32 v[78:79], v[14:15]
	v_mov_b64_e32 v[76:77], v[12:13]
	v_mov_b64_e32 v[74:75], v[10:11]
	v_mov_b64_e32 v[72:73], v[8:9]
	v_mov_b64_e32 v[70:71], v[6:7]
	v_mov_b64_e32 v[68:69], v[4:5]
	v_mov_b64_e32 v[66:67], v[2:3]
	v_mov_b64_e32 v[64:65], v[0:1]

.LBB0_4384:
	v_add3_u32 v0, s20, v135, v136
	s_waitcnt lgkmcnt(0)
	s_barrier
	v_lshrrev_b64 v[232:233], s2, v[120:121]
	v_and_b32_e32 v232, 1, v232
	v_cmp_eq_u32_e64 s[84:85], 0, v232
	s_nop 1
	v_cndmask_b32_e64 v212, v228, v185, s[84:85]
	v_cndmask_b32_e64 v213, v228, v185, s[84:85]
	v_cndmask_b32_e64 v214, v228, v185, s[84:85]
	v_cndmask_b32_e64 v215, v228, v185, s[84:85]
	v_cndmask_b32_e64 v216, v228, v185, s[84:85]
	v_cndmask_b32_e64 v217, v228, v185, s[84:85]
	v_cndmask_b32_e64 v218, v228, v185, s[84:85]
	v_cndmask_b32_e64 v219, v228, v185, s[84:85]
	v_cndmask_b32_e64 v220, v228, v185, s[84:85]
	v_cndmask_b32_e64 v221, v228, v185, s[84:85]
	v_cndmask_b32_e64 v222, v228, v185, s[84:85]
	v_cndmask_b32_e64 v223, v228, v185, s[84:85]
	v_cndmask_b32_e64 v224, v228, v185, s[84:85]
	v_cndmask_b32_e64 v225, v228, v185, s[84:85]
	v_cndmask_b32_e64 v226, v228, v185, s[84:85]
	v_cndmask_b32_e64 v227, v228, v185, s[84:85]
	ds_read_b128 v[2:5], v0
	ds_read_b128 v[18:21], v0 offset:32
	s_waitcnt lgkmcnt(1)
	v_mfma_f32_32x32x16_bf16 v[96:111], v[2:5], v[144:147], v[212:227]
	ds_read_b128 v[2:5], v0 offset:4608
	ds_read_b128 v[22:25], v0 offset:4640
	s_cmp_le_i32 s15, s48
	s_waitcnt lgkmcnt(1)
	v_mfma_f32_32x32x16_bf16 v[2:17], v[2:5], v[144:147], v[212:227]
	v_mfma_f32_32x32x16_bf16 v[96:111], v[18:21], v[148:151], v[96:111]
	s_waitcnt lgkmcnt(0)
	v_mfma_f32_32x32x16_bf16 v[2:17], v[22:25], v[148:151], v[2:17]
	ds_read_b128 v[18:21], v0 offset:64
	ds_read_b128 v[22:25], v0 offset:96
	s_waitcnt lgkmcnt(1)
	v_mfma_f32_32x32x16_bf16 v[96:111], v[18:21], v[152:155], v[96:111]
	ds_read_b128 v[18:21], v0 offset:4672
	ds_read_b128 v[26:29], v0 offset:4704
	s_waitcnt lgkmcnt(1)
	v_mfma_f32_32x32x16_bf16 v[2:17], v[18:21], v[152:155], v[2:17]
	v_mfma_f32_32x32x16_bf16 v[96:111], v[22:25], v[156:159], v[96:111]
	s_waitcnt lgkmcnt(0)
	v_mfma_f32_32x32x16_bf16 v[2:17], v[26:29], v[156:159], v[2:17]
	s_cbranch_scc1 .LBB0_4386
	v_add_u32_e32 v0, s15, v133
	v_subrev_u32_e32 v18, 63, v0
	v_cmp_le_i32_e32 vcc, v18, v132
	s_nop 5
	v_cndmask_b32_e32 v96, v185, v96, vcc
	v_cmp_lt_i32_e32 vcc, v18, v132
	v_subrev_u32_e32 v18, 61, v0
	s_nop 0
	v_cndmask_b32_e32 v97, v185, v97, vcc
	v_cmp_le_i32_e32 vcc, v18, v132
	v_subrev_u32_e32 v18, 60, v0
	s_nop 0
	v_cndmask_b32_e32 v98, v185, v98, vcc
	v_cmp_le_i32_e32 vcc, v18, v132
	v_subrev_u32_e32 v18, 55, v0
	s_nop 0
	v_cndmask_b32_e32 v99, v185, v99, vcc
	v_cmp_le_i32_e32 vcc, v18, v132
	v_subrev_u32_e32 v18, 54, v0
	s_nop 0
	v_cndmask_b32_e32 v100, v185, v100, vcc
	v_cmp_le_i32_e32 vcc, v18, v132
	v_subrev_u32_e32 v18, 53, v0
	s_nop 0
	v_cndmask_b32_e32 v101, v185, v101, vcc
	v_cmp_le_i32_e32 vcc, v18, v132
	v_subrev_u32_e32 v18, 52, v0
	s_nop 0
	v_cndmask_b32_e32 v102, v185, v102, vcc
	v_cmp_le_i32_e32 vcc, v18, v132
	v_subrev_u32_e32 v18, 47, v0
	s_nop 0
	v_cndmask_b32_e32 v103, v185, v103, vcc
	v_cmp_le_i32_e32 vcc, v18, v132
	v_subrev_u32_e32 v18, 46, v0
	s_nop 0
	v_cndmask_b32_e32 v104, v185, v104, vcc
	v_cmp_le_i32_e32 vcc, v18, v132
	v_subrev_u32_e32 v18, 45, v0
	s_nop 0
	v_cndmask_b32_e32 v105, v185, v105, vcc
	v_cmp_le_i32_e32 vcc, v18, v132
	v_subrev_u32_e32 v18, 44, v0
	s_nop 0
	v_cndmask_b32_e32 v106, v185, v106, vcc
	v_cmp_le_i32_e32 vcc, v18, v132
	v_subrev_u32_e32 v18, 39, v0
	s_nop 0
	v_cndmask_b32_e32 v107, v185, v107, vcc
	v_cmp_le_i32_e32 vcc, v18, v132
	v_subrev_u32_e32 v18, 38, v0
	s_nop 0
	v_cndmask_b32_e32 v108, v185, v108, vcc
	v_cmp_le_i32_e32 vcc, v18, v132
	v_subrev_u32_e32 v18, 37, v0
	s_nop 0
	v_cndmask_b32_e32 v109, v185, v109, vcc
	v_cmp_le_i32_e32 vcc, v18, v132
	v_subrev_u32_e32 v18, 36, v0
	s_nop 0
	v_cndmask_b32_e32 v110, v185, v110, vcc
	v_cmp_le_i32_e32 vcc, v18, v132
	v_subrev_u32_e32 v18, 31, v0
	s_nop 0
	v_cndmask_b32_e32 v111, v185, v111, vcc
	v_cmp_le_i32_e32 vcc, v18, v132
	v_subrev_u32_e32 v18, 30, v0
	s_nop 0
	v_cndmask_b32_e32 v2, v185, v2, vcc
	v_cmp_le_i32_e32 vcc, v18, v132
	v_subrev_u32_e32 v18, 29, v0
	s_nop 0
	v_cndmask_b32_e32 v3, v185, v3, vcc
	v_cmp_le_i32_e32 vcc, v18, v132
	v_subrev_u32_e32 v18, 28, v0
	s_nop 0
	v_cndmask_b32_e32 v4, v185, v4, vcc
	v_cmp_le_i32_e32 vcc, v18, v132
	v_subrev_u32_e32 v18, 23, v0
	s_nop 0
	v_cndmask_b32_e32 v5, v185, v5, vcc
	v_cmp_le_i32_e32 vcc, v18, v132
	v_subrev_u32_e32 v18, 22, v0
	s_nop 0
	v_cndmask_b32_e32 v6, v185, v6, vcc
	v_cmp_le_i32_e32 vcc, v18, v132
	v_subrev_u32_e32 v18, 21, v0
	s_nop 0
	v_cndmask_b32_e32 v7, v185, v7, vcc
	v_cmp_le_i32_e32 vcc, v18, v132
	v_subrev_u32_e32 v18, 20, v0
	s_nop 0
	v_cndmask_b32_e32 v8, v185, v8, vcc
	v_cmp_le_i32_e32 vcc, v18, v132
	v_add_u32_e32 v18, -15, v0
	s_nop 0
	v_cndmask_b32_e32 v9, v185, v9, vcc
	v_cmp_le_i32_e32 vcc, v18, v132
	v_add_u32_e32 v18, -14, v0
	s_nop 0
	v_cndmask_b32_e32 v10, v185, v10, vcc
	v_cmp_le_i32_e32 vcc, v18, v132
	v_add_u32_e32 v18, -13, v0
	s_nop 0
	v_cndmask_b32_e32 v11, v185, v11, vcc
	v_cmp_le_i32_e32 vcc, v18, v132
	v_add_u32_e32 v18, -12, v0
	s_nop 0
	v_cndmask_b32_e32 v12, v185, v12, vcc
	v_cmp_le_i32_e32 vcc, v18, v132
	v_add_u32_e32 v18, -7, v0
	s_nop 0
	v_cndmask_b32_e32 v13, v185, v13, vcc
	v_cmp_le_i32_e32 vcc, v18, v132
	v_add_u32_e32 v18, -6, v0
	s_nop 0
	v_cndmask_b32_e32 v14, v185, v14, vcc
	v_cmp_le_i32_e32 vcc, v18, v132
	v_add_u32_e32 v18, -5, v0
	v_add_u32_e32 v0, -4, v0
	v_cndmask_b32_e32 v15, v185, v15, vcc
	v_cmp_le_i32_e32 vcc, v18, v132
	s_nop 1
	v_cndmask_b32_e32 v16, v185, v16, vcc
	v_cmp_le_i32_e32 vcc, v0, v132
	s_nop 1
	v_cndmask_b32_e32 v17, v185, v17, vcc
.LBB0_4386:
	s_nop 8
	v_max3_f32 v0, v96, s66, v97
	v_max3_f32 v0, v0, v98, v99
	v_max3_f32 v0, v0, v100, v101
	v_max3_f32 v0, v0, v102, v103
	v_max3_f32 v0, v0, v104, v105
	v_max3_f32 v0, v0, v106, v107
	v_max3_f32 v0, v0, v108, v109
	v_max3_f32 v0, v0, v110, v111
	v_max3_f32 v0, v0, v2, v3
	v_max3_f32 v0, v0, v4, v5
	v_max3_f32 v0, v0, v6, v7
	v_max3_f32 v0, v0, v8, v9
	v_max3_f32 v0, v0, v10, v11
	v_max3_f32 v0, v0, v12, v13
	v_max3_f32 v0, v0, v14, v15
	v_max3_f32 v20, v0, v16, v17
	ds_bpermute_b32 v21, v175, v20
	v_lshrrev_b64 v[18:19], s2, v[120:121]
	v_and_b32_e32 v0, 1, v18
	v_cmp_eq_u64_e64 s[2:3], 0, v[0:1]
	s_waitcnt lgkmcnt(0)
	v_max_f32_e32 v18, v21, v21
	v_max_f32_e32 v18, v20, v18
	v_cndmask_b32_e64 v0, v18, v185, s[2:3]
	v_add_f32_e32 v18, 0x41000000, v229
	v_cmp_gt_f32_e32 vcc, v0, v18
	s_cbranch_vccz .LBB0_4388
	v_max_f32_e32 v0, v0, v0
	v_max_f32_e32 v230, v229, v229
	v_max_f32_e32 v230, v230, v0
	v_sub_f32_e32 v231, v230, v228
	v_sub_f32_e32 v0, v229, v230
	v_exp_f32_e32 v0, v0
	s_nop 0
	v_pk_mul_f32 v[94:95], v[94:95], v[0:1] op_sel_hi:[1,0]
	v_pk_mul_f32 v[92:93], v[92:93], v[0:1] op_sel_hi:[1,0]
	v_pk_mul_f32 v[90:91], v[90:91], v[0:1] op_sel_hi:[1,0]
	v_pk_mul_f32 v[88:89], v[88:89], v[0:1] op_sel_hi:[1,0]
	v_pk_mul_f32 v[86:87], v[86:87], v[0:1] op_sel_hi:[1,0]
	v_pk_mul_f32 v[84:85], v[84:85], v[0:1] op_sel_hi:[1,0]
	v_pk_mul_f32 v[82:83], v[82:83], v[0:1] op_sel_hi:[1,0]
	v_pk_mul_f32 v[80:81], v[80:81], v[0:1] op_sel_hi:[1,0]
	v_pk_mul_f32 v[78:79], v[78:79], v[0:1] op_sel_hi:[1,0]
	v_pk_mul_f32 v[76:77], v[76:77], v[0:1] op_sel_hi:[1,0]
	v_pk_mul_f32 v[74:75], v[74:75], v[0:1] op_sel_hi:[1,0]
	v_pk_mul_f32 v[72:73], v[72:73], v[0:1] op_sel_hi:[1,0]
	v_pk_mul_f32 v[70:71], v[70:71], v[0:1] op_sel_hi:[1,0]
	v_pk_mul_f32 v[68:69], v[68:69], v[0:1] op_sel_hi:[1,0]
	v_pk_mul_f32 v[66:67], v[66:67], v[0:1] op_sel_hi:[1,0]
	v_pk_mul_f32 v[64:65], v[64:65], v[0:1] op_sel_hi:[1,0]
	v_mul_f32_e32 v189, v189, v0
	v_mov_b32_e32 v139, v231
	v_xor_b32_e32 v230, 0x80000000, v231
	v_cmp_lt_f32_e32 vcc, 0xf0a18f08, v231
	s_nop 1
	v_cndmask_b32_e32 v230, 0, v230, vcc
	v_add_f32_e32 v229, v231, v230
	v_sub_f32_e32 v231, v230, v228
	v_mov_b32_e32 v228, v230
	v_add_f32_e32 v2, v231, v2
	v_add_f32_e32 v3, v231, v3
	v_add_f32_e32 v4, v231, v4
	v_add_f32_e32 v5, v231, v5
	v_add_f32_e32 v6, v231, v6
	v_add_f32_e32 v7, v231, v7
	v_add_f32_e32 v8, v231, v8
	v_add_f32_e32 v9, v231, v9
	v_add_f32_e32 v10, v231, v10
	v_add_f32_e32 v11, v231, v11
	v_add_f32_e32 v12, v231, v12
	v_add_f32_e32 v13, v231, v13
	v_add_f32_e32 v14, v231, v14
	v_add_f32_e32 v15, v231, v15
	v_add_f32_e32 v16, v231, v16
	v_add_f32_e32 v17, v231, v17
	v_add_f32_e32 v96, v231, v96
	v_add_f32_e32 v97, v231, v97
	v_add_f32_e32 v98, v231, v98
	v_add_f32_e32 v99, v231, v99
	v_add_f32_e32 v100, v231, v100
	v_add_f32_e32 v101, v231, v101
	v_add_f32_e32 v102, v231, v102
	v_add_f32_e32 v103, v231, v103
	v_add_f32_e32 v104, v231, v104
	v_add_f32_e32 v105, v231, v105
	v_add_f32_e32 v106, v231, v106
	v_add_f32_e32 v107, v231, v107
	v_add_f32_e32 v108, v231, v108
	v_add_f32_e32 v109, v231, v109
	v_add_f32_e32 v110, v231, v110
	v_add_f32_e32 v111, v231, v111
.LBB0_4388:
	v_add_u32_e32 v19, s20, v134
	v_exp_f32_e32 v18, v96
	v_add3_u32 v22, v19, v137, v138
	v_exp_f32_e32 v19, v97
	v_exp_f32_e32 v21, v98
	v_exp_f32_e32 v23, v99
	v_add_f32_e32 v20, 0, v18
	v_exp_f32_e32 v24, v100
	v_add_f32_e32 v20, v19, v20
	v_exp_f32_e32 v25, v101
	v_add_f32_e32 v20, v21, v20
	v_exp_f32_e32 v26, v102
	v_add_f32_e32 v20, v23, v20
	v_exp_f32_e32 v27, v103
	v_add_f32_e32 v20, v24, v20
	v_exp_f32_e32 v28, v104
	v_add_f32_e32 v20, v25, v20
	v_exp_f32_e32 v29, v105
	v_add_f32_e32 v20, v26, v20
	v_exp_f32_e32 v30, v106
	v_add_f32_e32 v20, v27, v20
	v_exp_f32_e32 v31, v107
	v_add_f32_e32 v20, v28, v20
	v_exp_f32_e32 v96, v108
	v_add_f32_e32 v20, v29, v20
	v_exp_f32_e32 v97, v109
	v_add_f32_e32 v20, v30, v20
	v_exp_f32_e32 v98, v110
	v_add_f32_e32 v20, v31, v20
	v_exp_f32_e32 v99, v111
	v_add_f32_e32 v20, v96, v20
	v_exp_f32_e32 v100, v2
	v_add_f32_e32 v2, v97, v20
	v_exp_f32_e32 v101, v3
	v_add_f32_e32 v2, v98, v2
	v_exp_f32_e32 v102, v4
	v_add_f32_e32 v2, v99, v2
	v_exp_f32_e32 v103, v5
	v_add_f32_e32 v2, v100, v2
	v_exp_f32_e32 v104, v6
	v_add_f32_e32 v2, v101, v2
	v_add_f32_e32 v2, v102, v2
	v_add_f32_e32 v2, v103, v2
	v_add_f32_e32 v105, v104, v2
	v_exp_f32_e32 v106, v7
	v_exp_f32_e32 v107, v8
	v_exp_f32_e32 v108, v9
	ds_read_b64_tr_b16 v[2:3], v22 offset:9216
	ds_read_b64_tr_b16 v[4:5], v22 offset:10752
	v_exp_f32_e32 v109, v10
	v_cvt_pk_bf16_f32 v7, v21, v23
	v_cvt_pk_bf16_f32 v6, v18, v19
	ds_read_b64_tr_b16 v[20:21], v22 offset:10816
	ds_read_b64_tr_b16 v[18:19], v22 offset:9280
	v_cvt_pk_bf16_f32 v9, v26, v27
	v_cvt_pk_bf16_f32 v8, v24, v25
	v_mov_b32_e32 v24, v11
	s_waitcnt lgkmcnt(2)
	v_mfma_f32_32x32x16_bf16 v[64:79], v[2:5], v[6:9], v[64:79]
	v_add_f32_e32 v2, v106, v105
	v_add_f32_e32 v2, v107, v2
	v_add_f32_e32 v2, v108, v2
	v_add_f32_e32 v23, v109, v2
	ds_read_b64_tr_b16 v[2:3], v22 offset:12288
	ds_read_b64_tr_b16 v[4:5], v22 offset:13824
	v_exp_f32_e32 v25, v12
	s_waitcnt lgkmcnt(2)
	v_mfma_f32_32x32x16_bf16 v[80:95], v[18:21], v[6:9], v[80:95]
	ds_read_b64_tr_b16 v[20:21], v22 offset:13888
	ds_read_b64_tr_b16 v[18:19], v22 offset:12352
	v_cvt_pk_bf16_f32 v9, v98, v99
	v_cvt_pk_bf16_f32 v8, v96, v97
	v_cvt_pk_bf16_f32 v7, v30, v31
	v_cvt_pk_bf16_f32 v6, v28, v29
	v_exp_f32_e32 v15, v15
	s_add_i32 s15, s15, 64
	s_waitcnt lgkmcnt(2)
	v_mfma_f32_32x32x16_bf16 v[64:79], v[2:5], v[6:9], v[64:79]
	v_exp_f32_e32 v26, v13
	v_exp_f32_e32 v14, v14
	ds_read_b64_tr_b16 v[2:3], v22 offset:15360
	ds_read_b64_tr_b16 v[4:5], v22 offset:16896
	ds_read_b64_tr_b16 v[12:13], v22 offset:16960
	ds_read_b64_tr_b16 v[10:11], v22 offset:15424
	v_lshl_add_u64 v[126:127], v[126:127], 0, s[36:37]
	s_waitcnt lgkmcnt(4)
	v_mfma_f32_32x32x16_bf16 v[80:95], v[18:21], v[6:9], v[80:95]
	v_cvt_pk_bf16_f32 v9, v107, v108
	v_cvt_pk_bf16_f32 v8, v104, v106
	v_cvt_pk_bf16_f32 v7, v102, v103
	v_cvt_pk_bf16_f32 v6, v100, v101
	s_cmp_eq_u32 s9, s12
	v_lshl_add_u64 v[128:129], v[128:129], 0, s[36:37]
	s_waitcnt lgkmcnt(2)
	v_mfma_f32_32x32x16_bf16 v[64:79], v[2:5], v[6:9], v[64:79]
	v_exp_f32_e32 v16, v16
	v_exp_f32_e32 v0, v17
	ds_read_b64_tr_b16 v[2:3], v22 offset:18432
	ds_read_b64_tr_b16 v[4:5], v22 offset:19968
	v_exp_f32_e32 v17, v24
	s_waitcnt lgkmcnt(2)
	v_mfma_f32_32x32x16_bf16 v[80:95], v[10:13], v[6:9], v[80:95]
	ds_read_b64_tr_b16 v[12:13], v22 offset:20032
	ds_read_b64_tr_b16 v[10:11], v22 offset:18496
	v_cvt_pk_bf16_f32 v9, v16, v0
	v_cvt_pk_bf16_f32 v8, v14, v15
	v_cvt_pk_bf16_f32 v7, v25, v26
	v_cvt_pk_bf16_f32 v6, v109, v17
	s_waitcnt lgkmcnt(2)
	s_nop 0
	v_mfma_f32_32x32x16_bf16 v[64:79], v[2:5], v[6:9], v[64:79]
	v_add_f32_e32 v2, v17, v23
	v_add_f32_e32 v2, v25, v2
	v_add_f32_e32 v2, v26, v2
	v_add_f32_e32 v2, v14, v2
	v_add_f32_e32 v2, v15, v2
	v_add_f32_e32 v2, v16, v2
	v_add_f32_e32 v0, v0, v2
	s_waitcnt lgkmcnt(0)
	v_mfma_f32_32x32x16_bf16 v[80:95], v[10:13], v[6:9], v[80:95]
	v_add_f32_e32 v189, v189, v0
	s_cbranch_scc1 .LBB0_4391
	s_mov_b64 s[2:3], s[12:13]
	s_branch .LBB0_4382
